# NAT q/k GEMM epilogue (rope rotation) as a contiguous fast path: rope quads loaded once per row section, dwordx4 stores
# baseline (speedup 1.0000x reference)
.Llru_no:
	s_cmp_lg_u32 s79, 19
	s_cbranch_scc1 .Lnat_no
	s_cmpk_gt_u32 s27, 0x7ff
	s_cbranch_scc1 .Lnat_no
	v_lshlrev_b64 v[244:245], 11, v[138:139]
	v_lshl_add_u64 v[244:245], s[48:49], 0, v[244:245]
	v_mbcnt_lo_u32_b32 v246, -1, 0
	v_mbcnt_hi_u32_b32 v246, -1, v246
	v_and_b32_e32 v246, 16, v246
	v_lshrrev_b32_e32 v247, 1, v246
	v_add_u32_e32 v246, v246, v247
	v_and_b32_e32 v247, 0x3ff, v136
	v_lshl_add_u32 v246, v247, 1, v246
	v_mov_b32_e32 v247, 0
	v_lshl_add_u64 v[244:245], v[246:247], 0, v[244:245]
	s_ashr_i32 s2, s67, 2
	s_add_i32 s2, s2, 1
	s_mul_i32 s2, s2, 0x2100000
	s_mov_b32 s3, 0
	v_lshl_add_u64 v[244:245], v[244:245], 0, s[2:3]
	v_bfe_u32 v246, v136, 5, 1
	s_nop 1
	v_readfirstlane_b32 s3, v246
	s_nop 1
	v_and_b32_e32 v202, 63, v138
	v_bfe_u32 v203, v138, 6, 7
	s_cmp_lg_u32 s3, 0
	s_cselect_b64 vcc, -1, 0
	s_nop 3
	v_cndmask_b32_e32 v202, v203, v202, vcc
	v_and_b32_e32 v203, 15, v136
	v_lshlrev_b32_e32 v203, 3, v203
	v_lshl_or_b32 v202, v202, 7, v203
	v_mov_b32_e32 v203, 0
	v_lshl_add_u64 v[202:203], v[202:203], 0, s[50:51]
	s_cmp_lg_u32 s3, 0
	s_mov_b32 s2, 0x0
	s_cselect_b32 s2, 0x0, s2
	v_add_co_u32_e32 v246, vcc, s2, v202
	v_addc_co_u32_e32 v247, vcc, 0, v203, vcc
	global_load_dwordx4 v[214:217], v[246:247], off
	global_load_dwordx4 v[218:221], v[246:247], off offset:16
	s_waitcnt vmcnt(0)
	v_mov_b32_e32 v206, v214
	v_mov_b32_e32 v207, v216
	v_mov_b32_e32 v210, v215
	v_mov_b32_e32 v211, v217
	v_mov_b32_e32 v208, v218
	v_mov_b32_e32 v209, v220
	v_mov_b32_e32 v212, v219
	v_mov_b32_e32 v213, v221
	v_pk_mul_f32 v[222:223], v[122:123], v[212:213]
	v_pk_mul_f32 v[224:225], v[120:121], v[210:211]
	v_pk_fma_f32 v[222:223], v[126:127], v[208:209], v[222:223] neg_lo:[0,0,1] neg_hi:[0,0,1]
	v_pk_fma_f32 v[224:225], v[124:125], v[206:207], v[224:225] neg_lo:[0,0,1] neg_hi:[0,0,1]
	v_cvt_pk_bf16_f32 v230, v224, v225
	v_cvt_pk_bf16_f32 v231, v222, v223
	v_pk_mul_f32 v[222:223], v[122:123], v[208:209]
	v_pk_mul_f32 v[224:225], v[120:121], v[206:207]
	v_pk_fma_f32 v[222:223], v[126:127], v[212:213], v[222:223]
	v_pk_fma_f32 v[224:225], v[124:125], v[210:211], v[224:225]
	v_cvt_pk_bf16_f32 v232, v224, v225
	v_cvt_pk_bf16_f32 v233, v222, v223
	s_nop 1
	v_permlane16_swap_b32 v230, v232
	v_permlane16_swap_b32 v231, v233
	global_store_dwordx4 v[244:245], v[230:233], off
	v_pk_mul_f32 v[222:223], v[114:115], v[212:213]
	v_pk_mul_f32 v[224:225], v[112:113], v[210:211]
	v_pk_fma_f32 v[222:223], v[118:119], v[208:209], v[222:223] neg_lo:[0,0,1] neg_hi:[0,0,1]
	v_pk_fma_f32 v[224:225], v[116:117], v[206:207], v[224:225] neg_lo:[0,0,1] neg_hi:[0,0,1]
	v_cvt_pk_bf16_f32 v234, v224, v225
	v_cvt_pk_bf16_f32 v235, v222, v223
	v_pk_mul_f32 v[222:223], v[114:115], v[208:209]
	v_pk_mul_f32 v[224:225], v[112:113], v[206:207]
	v_pk_fma_f32 v[222:223], v[118:119], v[212:213], v[222:223]
	v_pk_fma_f32 v[224:225], v[116:117], v[210:211], v[224:225]
	v_cvt_pk_bf16_f32 v236, v224, v225
	v_cvt_pk_bf16_f32 v237, v222, v223
	v_add_co_u32_e32 v246, vcc, 0x100, v244
	v_addc_co_u32_e32 v247, vcc, 0, v245, vcc
	v_permlane16_swap_b32 v234, v236
	v_permlane16_swap_b32 v235, v237
	global_store_dwordx4 v[246:247], v[234:237], off
	s_cmp_lg_u32 s3, 0
	s_mov_b32 s2, 0x0
	s_cselect_b32 s2, 0x800, s2
	v_add_co_u32_e32 v246, vcc, s2, v202
	v_addc_co_u32_e32 v247, vcc, 0, v203, vcc
	global_load_dwordx4 v[214:217], v[246:247], off
	global_load_dwordx4 v[218:221], v[246:247], off offset:16
	s_waitcnt vmcnt(0)
	v_mov_b32_e32 v206, v214
	v_mov_b32_e32 v207, v216
	v_mov_b32_e32 v210, v215
	v_mov_b32_e32 v211, v217
	v_mov_b32_e32 v208, v218
	v_mov_b32_e32 v209, v220
	v_mov_b32_e32 v212, v219
	v_mov_b32_e32 v213, v221
	v_pk_mul_f32 v[222:223], v[106:107], v[212:213]
	v_pk_mul_f32 v[224:225], v[104:105], v[210:211]
	v_pk_fma_f32 v[222:223], v[110:111], v[208:209], v[222:223] neg_lo:[0,0,1] neg_hi:[0,0,1]
	v_pk_fma_f32 v[224:225], v[108:109], v[206:207], v[224:225] neg_lo:[0,0,1] neg_hi:[0,0,1]
	v_cvt_pk_bf16_f32 v230, v224, v225
	v_cvt_pk_bf16_f32 v231, v222, v223
	v_pk_mul_f32 v[222:223], v[106:107], v[208:209]
	v_pk_mul_f32 v[224:225], v[104:105], v[206:207]
	v_pk_fma_f32 v[222:223], v[110:111], v[212:213], v[222:223]
	v_pk_fma_f32 v[224:225], v[108:109], v[210:211], v[224:225]
	v_cvt_pk_bf16_f32 v232, v224, v225
	v_cvt_pk_bf16_f32 v233, v222, v223
	v_add_co_u32_e32 v246, vcc, 0x8000, v244
	v_addc_co_u32_e32 v247, vcc, 0, v245, vcc
	v_permlane16_swap_b32 v230, v232
	v_permlane16_swap_b32 v231, v233
	global_store_dwordx4 v[246:247], v[230:233], off
	v_pk_mul_f32 v[222:223], v[98:99], v[212:213]
	v_pk_mul_f32 v[224:225], v[96:97], v[210:211]
	v_pk_fma_f32 v[222:223], v[102:103], v[208:209], v[222:223] neg_lo:[0,0,1] neg_hi:[0,0,1]
	v_pk_fma_f32 v[224:225], v[100:101], v[206:207], v[224:225] neg_lo:[0,0,1] neg_hi:[0,0,1]
	v_cvt_pk_bf16_f32 v234, v224, v225
	v_cvt_pk_bf16_f32 v235, v222, v223
	v_pk_mul_f32 v[222:223], v[98:99], v[208:209]
	v_pk_mul_f32 v[224:225], v[96:97], v[206:207]
	v_pk_fma_f32 v[222:223], v[102:103], v[212:213], v[222:223]
	v_pk_fma_f32 v[224:225], v[100:101], v[210:211], v[224:225]
	v_cvt_pk_bf16_f32 v236, v224, v225
	v_cvt_pk_bf16_f32 v237, v222, v223
	v_add_co_u32_e32 v246, vcc, 0x8100, v244
	v_addc_co_u32_e32 v247, vcc, 0, v245, vcc
	v_permlane16_swap_b32 v234, v236
	v_permlane16_swap_b32 v235, v237
	global_store_dwordx4 v[246:247], v[234:237], off
	s_cmp_lg_u32 s3, 0
	s_mov_b32 s2, 0x0
	s_cselect_b32 s2, 0x1000, s2
	v_add_co_u32_e32 v246, vcc, s2, v202
	v_addc_co_u32_e32 v247, vcc, 0, v203, vcc
	global_load_dwordx4 v[214:217], v[246:247], off
	global_load_dwordx4 v[218:221], v[246:247], off offset:16
	s_waitcnt vmcnt(0)
	v_mov_b32_e32 v206, v214
	v_mov_b32_e32 v207, v216
	v_mov_b32_e32 v210, v215
	v_mov_b32_e32 v211, v217
	v_mov_b32_e32 v208, v218
	v_mov_b32_e32 v209, v220
	v_mov_b32_e32 v212, v219
	v_mov_b32_e32 v213, v221
	v_pk_mul_f32 v[222:223], v[90:91], v[212:213]
	v_pk_mul_f32 v[224:225], v[88:89], v[210:211]
	v_pk_fma_f32 v[222:223], v[94:95], v[208:209], v[222:223] neg_lo:[0,0,1] neg_hi:[0,0,1]
	v_pk_fma_f32 v[224:225], v[92:93], v[206:207], v[224:225] neg_lo:[0,0,1] neg_hi:[0,0,1]
	v_cvt_pk_bf16_f32 v230, v224, v225
	v_cvt_pk_bf16_f32 v231, v222, v223
	v_pk_mul_f32 v[222:223], v[90:91], v[208:209]
	v_pk_mul_f32 v[224:225], v[88:89], v[206:207]
	v_pk_fma_f32 v[222:223], v[94:95], v[212:213], v[222:223]
	v_pk_fma_f32 v[224:225], v[92:93], v[210:211], v[224:225]
	v_cvt_pk_bf16_f32 v232, v224, v225
	v_cvt_pk_bf16_f32 v233, v222, v223
	v_add_co_u32_e32 v246, vcc, 0x10000, v244
	v_addc_co_u32_e32 v247, vcc, 0, v245, vcc
	v_permlane16_swap_b32 v230, v232
	v_permlane16_swap_b32 v231, v233
	global_store_dwordx4 v[246:247], v[230:233], off
	v_pk_mul_f32 v[222:223], v[82:83], v[212:213]
	v_pk_mul_f32 v[224:225], v[80:81], v[210:211]
	v_pk_fma_f32 v[222:223], v[86:87], v[208:209], v[222:223] neg_lo:[0,0,1] neg_hi:[0,0,1]
	v_pk_fma_f32 v[224:225], v[84:85], v[206:207], v[224:225] neg_lo:[0,0,1] neg_hi:[0,0,1]
	v_cvt_pk_bf16_f32 v234, v224, v225
	v_cvt_pk_bf16_f32 v235, v222, v223
	v_pk_mul_f32 v[222:223], v[82:83], v[208:209]
	v_pk_mul_f32 v[224:225], v[80:81], v[206:207]
	v_pk_fma_f32 v[222:223], v[86:87], v[212:213], v[222:223]
	v_pk_fma_f32 v[224:225], v[84:85], v[210:211], v[224:225]
	v_cvt_pk_bf16_f32 v236, v224, v225
	v_cvt_pk_bf16_f32 v237, v222, v223
	v_add_co_u32_e32 v246, vcc, 0x10100, v244
	v_addc_co_u32_e32 v247, vcc, 0, v245, vcc
	v_permlane16_swap_b32 v234, v236
	v_permlane16_swap_b32 v235, v237
	global_store_dwordx4 v[246:247], v[234:237], off
	s_cmp_lg_u32 s3, 0
	s_mov_b32 s2, 0x0
	s_cselect_b32 s2, 0x1800, s2
	v_add_co_u32_e32 v246, vcc, s2, v202
	v_addc_co_u32_e32 v247, vcc, 0, v203, vcc
	global_load_dwordx4 v[214:217], v[246:247], off
	global_load_dwordx4 v[218:221], v[246:247], off offset:16
	s_waitcnt vmcnt(0)
	v_mov_b32_e32 v206, v214
	v_mov_b32_e32 v207, v216
	v_mov_b32_e32 v210, v215
	v_mov_b32_e32 v211, v217
	v_mov_b32_e32 v208, v218
	v_mov_b32_e32 v209, v220
	v_mov_b32_e32 v212, v219
	v_mov_b32_e32 v213, v221
	v_pk_mul_f32 v[222:223], v[74:75], v[212:213]
	v_pk_mul_f32 v[224:225], v[72:73], v[210:211]
	v_pk_fma_f32 v[222:223], v[78:79], v[208:209], v[222:223] neg_lo:[0,0,1] neg_hi:[0,0,1]
	v_pk_fma_f32 v[224:225], v[76:77], v[206:207], v[224:225] neg_lo:[0,0,1] neg_hi:[0,0,1]
	v_cvt_pk_bf16_f32 v230, v224, v225
	v_cvt_pk_bf16_f32 v231, v222, v223
	v_pk_mul_f32 v[222:223], v[74:75], v[208:209]
	v_pk_mul_f32 v[224:225], v[72:73], v[206:207]
	v_pk_fma_f32 v[222:223], v[78:79], v[212:213], v[222:223]
	v_pk_fma_f32 v[224:225], v[76:77], v[210:211], v[224:225]
	v_cvt_pk_bf16_f32 v232, v224, v225
	v_cvt_pk_bf16_f32 v233, v222, v223
	v_add_co_u32_e32 v246, vcc, 0x18000, v244
	v_addc_co_u32_e32 v247, vcc, 0, v245, vcc
	v_permlane16_swap_b32 v230, v232
	v_permlane16_swap_b32 v231, v233
	global_store_dwordx4 v[246:247], v[230:233], off
	v_pk_mul_f32 v[222:223], v[66:67], v[212:213]
	v_pk_mul_f32 v[224:225], v[64:65], v[210:211]
	v_pk_fma_f32 v[222:223], v[70:71], v[208:209], v[222:223] neg_lo:[0,0,1] neg_hi:[0,0,1]
	v_pk_fma_f32 v[224:225], v[68:69], v[206:207], v[224:225] neg_lo:[0,0,1] neg_hi:[0,0,1]
	v_cvt_pk_bf16_f32 v234, v224, v225
	v_cvt_pk_bf16_f32 v235, v222, v223
	v_pk_mul_f32 v[222:223], v[66:67], v[208:209]
	v_pk_mul_f32 v[224:225], v[64:65], v[206:207]
	v_pk_fma_f32 v[222:223], v[70:71], v[212:213], v[222:223]
	v_pk_fma_f32 v[224:225], v[68:69], v[210:211], v[224:225]
	v_cvt_pk_bf16_f32 v236, v224, v225
	v_cvt_pk_bf16_f32 v237, v222, v223
	v_add_co_u32_e32 v246, vcc, 0x18100, v244
	v_addc_co_u32_e32 v247, vcc, 0, v245, vcc
	v_permlane16_swap_b32 v234, v236
	v_permlane16_swap_b32 v235, v237
	global_store_dwordx4 v[246:247], v[234:237], off
	s_cmp_lg_u32 s3, 0
	s_mov_b32 s2, 0x100
	s_cselect_b32 s2, 0x0, s2
	v_add_co_u32_e32 v246, vcc, s2, v202
	v_addc_co_u32_e32 v247, vcc, 0, v203, vcc
	global_load_dwordx4 v[214:217], v[246:247], off
	global_load_dwordx4 v[218:221], v[246:247], off offset:16
	s_waitcnt vmcnt(0)
	v_mov_b32_e32 v206, v214
	v_mov_b32_e32 v207, v216
	v_mov_b32_e32 v210, v215
	v_mov_b32_e32 v211, v217
	v_mov_b32_e32 v208, v218
	v_mov_b32_e32 v209, v220
	v_mov_b32_e32 v212, v219
	v_mov_b32_e32 v213, v221
	v_pk_mul_f32 v[222:223], v[58:59], v[212:213]
	v_pk_mul_f32 v[224:225], v[56:57], v[210:211]
	v_pk_fma_f32 v[222:223], v[62:63], v[208:209], v[222:223] neg_lo:[0,0,1] neg_hi:[0,0,1]
	v_pk_fma_f32 v[224:225], v[60:61], v[206:207], v[224:225] neg_lo:[0,0,1] neg_hi:[0,0,1]
	v_cvt_pk_bf16_f32 v230, v224, v225
	v_cvt_pk_bf16_f32 v231, v222, v223
	v_pk_mul_f32 v[222:223], v[58:59], v[208:209]
	v_pk_mul_f32 v[224:225], v[56:57], v[206:207]
	v_pk_fma_f32 v[222:223], v[62:63], v[212:213], v[222:223]
	v_pk_fma_f32 v[224:225], v[60:61], v[210:211], v[224:225]
	v_cvt_pk_bf16_f32 v232, v224, v225
	v_cvt_pk_bf16_f32 v233, v222, v223
	v_add_co_u32_e32 v246, vcc, 0x40000, v244
	v_addc_co_u32_e32 v247, vcc, 0, v245, vcc
	v_permlane16_swap_b32 v230, v232
	v_permlane16_swap_b32 v231, v233
	global_store_dwordx4 v[246:247], v[230:233], off
	v_pk_mul_f32 v[222:223], v[50:51], v[212:213]
	v_pk_mul_f32 v[224:225], v[48:49], v[210:211]
	v_pk_fma_f32 v[222:223], v[54:55], v[208:209], v[222:223] neg_lo:[0,0,1] neg_hi:[0,0,1]
	v_pk_fma_f32 v[224:225], v[52:53], v[206:207], v[224:225] neg_lo:[0,0,1] neg_hi:[0,0,1]
	v_cvt_pk_bf16_f32 v234, v224, v225
	v_cvt_pk_bf16_f32 v235, v222, v223
	v_pk_mul_f32 v[222:223], v[50:51], v[208:209]
	v_pk_mul_f32 v[224:225], v[48:49], v[206:207]
	v_pk_fma_f32 v[222:223], v[54:55], v[212:213], v[222:223]
	v_pk_fma_f32 v[224:225], v[52:53], v[210:211], v[224:225]
	v_cvt_pk_bf16_f32 v236, v224, v225
	v_cvt_pk_bf16_f32 v237, v222, v223
	v_add_co_u32_e32 v246, vcc, 0x40100, v244
	v_addc_co_u32_e32 v247, vcc, 0, v245, vcc
	v_permlane16_swap_b32 v234, v236
	v_permlane16_swap_b32 v235, v237
	global_store_dwordx4 v[246:247], v[234:237], off
	s_cmp_lg_u32 s3, 0
	s_mov_b32 s2, 0x100
	s_cselect_b32 s2, 0x800, s2
	v_add_co_u32_e32 v246, vcc, s2, v202
	v_addc_co_u32_e32 v247, vcc, 0, v203, vcc
	global_load_dwordx4 v[214:217], v[246:247], off
	global_load_dwordx4 v[218:221], v[246:247], off offset:16
	s_waitcnt vmcnt(0)
	v_mov_b32_e32 v206, v214
	v_mov_b32_e32 v207, v216
	v_mov_b32_e32 v210, v215
	v_mov_b32_e32 v211, v217
	v_mov_b32_e32 v208, v218
	v_mov_b32_e32 v209, v220
	v_mov_b32_e32 v212, v219
	v_mov_b32_e32 v213, v221
	v_pk_mul_f32 v[222:223], v[42:43], v[212:213]
	v_pk_mul_f32 v[224:225], v[40:41], v[210:211]
	v_pk_fma_f32 v[222:223], v[46:47], v[208:209], v[222:223] neg_lo:[0,0,1] neg_hi:[0,0,1]
	v_pk_fma_f32 v[224:225], v[44:45], v[206:207], v[224:225] neg_lo:[0,0,1] neg_hi:[0,0,1]
	v_cvt_pk_bf16_f32 v230, v224, v225
	v_cvt_pk_bf16_f32 v231, v222, v223
	v_pk_mul_f32 v[222:223], v[42:43], v[208:209]
	v_pk_mul_f32 v[224:225], v[40:41], v[206:207]
	v_pk_fma_f32 v[222:223], v[46:47], v[212:213], v[222:223]
	v_pk_fma_f32 v[224:225], v[44:45], v[210:211], v[224:225]
	v_cvt_pk_bf16_f32 v232, v224, v225
	v_cvt_pk_bf16_f32 v233, v222, v223
	v_add_co_u32_e32 v246, vcc, 0x48000, v244
	v_addc_co_u32_e32 v247, vcc, 0, v245, vcc
	v_permlane16_swap_b32 v230, v232
	v_permlane16_swap_b32 v231, v233
	global_store_dwordx4 v[246:247], v[230:233], off
	v_pk_mul_f32 v[222:223], v[34:35], v[212:213]
	v_pk_mul_f32 v[224:225], v[32:33], v[210:211]
	v_pk_fma_f32 v[222:223], v[38:39], v[208:209], v[222:223] neg_lo:[0,0,1] neg_hi:[0,0,1]
	v_pk_fma_f32 v[224:225], v[36:37], v[206:207], v[224:225] neg_lo:[0,0,1] neg_hi:[0,0,1]
	v_cvt_pk_bf16_f32 v234, v224, v225
	v_cvt_pk_bf16_f32 v235, v222, v223
	v_pk_mul_f32 v[222:223], v[34:35], v[208:209]
	v_pk_mul_f32 v[224:225], v[32:33], v[206:207]
	v_pk_fma_f32 v[222:223], v[38:39], v[212:213], v[222:223]
	v_pk_fma_f32 v[224:225], v[36:37], v[210:211], v[224:225]
	v_cvt_pk_bf16_f32 v236, v224, v225
	v_cvt_pk_bf16_f32 v237, v222, v223
	v_add_co_u32_e32 v246, vcc, 0x48100, v244
	v_addc_co_u32_e32 v247, vcc, 0, v245, vcc
	v_permlane16_swap_b32 v234, v236
	v_permlane16_swap_b32 v235, v237
	global_store_dwordx4 v[246:247], v[234:237], off
	s_cmp_lg_u32 s3, 0
	s_mov_b32 s2, 0x100
	s_cselect_b32 s2, 0x1000, s2
	v_add_co_u32_e32 v246, vcc, s2, v202
	v_addc_co_u32_e32 v247, vcc, 0, v203, vcc
	global_load_dwordx4 v[214:217], v[246:247], off
	global_load_dwordx4 v[218:221], v[246:247], off offset:16
	s_waitcnt vmcnt(0)
	v_mov_b32_e32 v206, v214
	v_mov_b32_e32 v207, v216
	v_mov_b32_e32 v210, v215
	v_mov_b32_e32 v211, v217
	v_mov_b32_e32 v208, v218
	v_mov_b32_e32 v209, v220
	v_mov_b32_e32 v212, v219
	v_mov_b32_e32 v213, v221
	v_pk_mul_f32 v[222:223], v[26:27], v[212:213]
	v_pk_mul_f32 v[224:225], v[24:25], v[210:211]
	v_pk_fma_f32 v[222:223], v[30:31], v[208:209], v[222:223] neg_lo:[0,0,1] neg_hi:[0,0,1]
	v_pk_fma_f32 v[224:225], v[28:29], v[206:207], v[224:225] neg_lo:[0,0,1] neg_hi:[0,0,1]
	v_cvt_pk_bf16_f32 v230, v224, v225
	v_cvt_pk_bf16_f32 v231, v222, v223
	v_pk_mul_f32 v[222:223], v[26:27], v[208:209]
	v_pk_mul_f32 v[224:225], v[24:25], v[206:207]
	v_pk_fma_f32 v[222:223], v[30:31], v[212:213], v[222:223]
	v_pk_fma_f32 v[224:225], v[28:29], v[210:211], v[224:225]
	v_cvt_pk_bf16_f32 v232, v224, v225
	v_cvt_pk_bf16_f32 v233, v222, v223
	v_add_co_u32_e32 v246, vcc, 0x50000, v244
	v_addc_co_u32_e32 v247, vcc, 0, v245, vcc
	v_permlane16_swap_b32 v230, v232
	v_permlane16_swap_b32 v231, v233
	global_store_dwordx4 v[246:247], v[230:233], off
	v_pk_mul_f32 v[222:223], v[18:19], v[212:213]
	v_pk_mul_f32 v[224:225], v[16:17], v[210:211]
	v_pk_fma_f32 v[222:223], v[22:23], v[208:209], v[222:223] neg_lo:[0,0,1] neg_hi:[0,0,1]
	v_pk_fma_f32 v[224:225], v[20:21], v[206:207], v[224:225] neg_lo:[0,0,1] neg_hi:[0,0,1]
	v_cvt_pk_bf16_f32 v234, v224, v225
	v_cvt_pk_bf16_f32 v235, v222, v223
	v_pk_mul_f32 v[222:223], v[18:19], v[208:209]
	v_pk_mul_f32 v[224:225], v[16:17], v[206:207]
	v_pk_fma_f32 v[222:223], v[22:23], v[212:213], v[222:223]
	v_pk_fma_f32 v[224:225], v[20:21], v[210:211], v[224:225]
	v_cvt_pk_bf16_f32 v236, v224, v225
	v_cvt_pk_bf16_f32 v237, v222, v223
	v_add_co_u32_e32 v246, vcc, 0x50100, v244
	v_addc_co_u32_e32 v247, vcc, 0, v245, vcc
	v_permlane16_swap_b32 v234, v236
	v_permlane16_swap_b32 v235, v237
	global_store_dwordx4 v[246:247], v[234:237], off
	s_cmp_lg_u32 s3, 0
	s_mov_b32 s2, 0x100
	s_cselect_b32 s2, 0x1800, s2
	v_add_co_u32_e32 v246, vcc, s2, v202
	v_addc_co_u32_e32 v247, vcc, 0, v203, vcc
	global_load_dwordx4 v[214:217], v[246:247], off
	global_load_dwordx4 v[218:221], v[246:247], off offset:16
	s_waitcnt vmcnt(0)
	v_mov_b32_e32 v206, v214
	v_mov_b32_e32 v207, v216
	v_mov_b32_e32 v210, v215
	v_mov_b32_e32 v211, v217
	v_mov_b32_e32 v208, v218
	v_mov_b32_e32 v209, v220
	v_mov_b32_e32 v212, v219
	v_mov_b32_e32 v213, v221
	v_pk_mul_f32 v[222:223], v[10:11], v[212:213]
	v_pk_mul_f32 v[224:225], v[8:9], v[210:211]
	v_pk_fma_f32 v[222:223], v[14:15], v[208:209], v[222:223] neg_lo:[0,0,1] neg_hi:[0,0,1]
	v_pk_fma_f32 v[224:225], v[12:13], v[206:207], v[224:225] neg_lo:[0,0,1] neg_hi:[0,0,1]
	v_cvt_pk_bf16_f32 v230, v224, v225
	v_cvt_pk_bf16_f32 v231, v222, v223
	v_pk_mul_f32 v[222:223], v[10:11], v[208:209]
	v_pk_mul_f32 v[224:225], v[8:9], v[206:207]
	v_pk_fma_f32 v[222:223], v[14:15], v[212:213], v[222:223]
	v_pk_fma_f32 v[224:225], v[12:13], v[210:211], v[224:225]
	v_cvt_pk_bf16_f32 v232, v224, v225
	v_cvt_pk_bf16_f32 v233, v222, v223
	v_add_co_u32_e32 v246, vcc, 0x58000, v244
	v_addc_co_u32_e32 v247, vcc, 0, v245, vcc
	v_permlane16_swap_b32 v230, v232
	v_permlane16_swap_b32 v231, v233
	global_store_dwordx4 v[246:247], v[230:233], off
	v_pk_mul_f32 v[222:223], v[2:3], v[212:213]
	v_pk_mul_f32 v[224:225], v[0:1], v[210:211]
	v_pk_fma_f32 v[222:223], v[6:7], v[208:209], v[222:223] neg_lo:[0,0,1] neg_hi:[0,0,1]
	v_pk_fma_f32 v[224:225], v[4:5], v[206:207], v[224:225] neg_lo:[0,0,1] neg_hi:[0,0,1]
	v_cvt_pk_bf16_f32 v234, v224, v225
	v_cvt_pk_bf16_f32 v235, v222, v223
	v_pk_mul_f32 v[222:223], v[2:3], v[208:209]
	v_pk_mul_f32 v[224:225], v[0:1], v[206:207]
	v_pk_fma_f32 v[222:223], v[6:7], v[212:213], v[222:223]
	v_pk_fma_f32 v[224:225], v[4:5], v[210:211], v[224:225]
	v_cvt_pk_bf16_f32 v236, v224, v225
	v_cvt_pk_bf16_f32 v237, v222, v223
	v_add_co_u32_e32 v246, vcc, 0x58100, v244
	v_addc_co_u32_e32 v247, vcc, 0, v245, vcc
	v_permlane16_swap_b32 v234, v236
	v_permlane16_swap_b32 v235, v237
	global_store_dwordx4 v[246:247], v[234:237], off
	s_branch .LBB0_1065
